# FFN gate-up/down GEMM code moved 192 bytes (s_nop padding before the phase): placement
# baseline (speedup 1.0000x reference)
.LBB0_1056:
	v_readlane_b32 s0, v253, 59
	v_mov_b32_e32 v10, v173
	v_readlane_b32 s1, v253, 60
	s_andn2_b64 vcc, exec, s[0:1]
	v_readfirstlane_b32 s0, v10
	s_cbranch_vccnz .LBB0_1072
	v_lshlrev_b32_e32 v0, 4, v10
	v_add_u32_e32 v1, 0x2000, v0
	v_ashrrev_i32_e32 v2, 31, v1
	v_lshrrev_b32_e32 v2, 22, v2
	v_add_u32_e32 v2, v1, v2
	v_ashrrev_i32_e32 v4, 10, v2
	v_mul_i32_i24_e32 v2, 0x400, v4
	v_sub_u32_e32 v1, v1, v2
	v_lshrrev_b32_e32 v2, 4, v1
	v_bitop3_b32 v1, v2, v1, 32 bitop3:0x6c
	v_ashrrev_i32_e32 v2, 31, v1
	v_lshrrev_b32_e32 v2, 26, v2
	v_add_u32_e32 v2, v1, v2
	v_lshlrev_b32_e32 v3, 3, v4
	v_ashrrev_i32_e32 v5, 6, v2
	v_and_b32_e32 v3, -16, v3
	v_add_u32_e32 v3, v5, v3
	v_and_b32_e32 v6, 3, v5
	s_mov_b32 s3, 0x1fffe0
	v_lshrrev_b32_e32 v7, 2, v3
	v_lshlrev_b32_e32 v8, 1, v3
	v_and_b32_e32 v2, 0xc0, v2
	v_and_or_b32 v6, v3, s3, v6
	v_and_b32_e32 v7, 4, v7
	v_and_b32_e32 v8, 24, v8
	v_sub_u32_e32 v1, v1, v2
	v_mov_b32_e32 v12, 1
	v_or3_b32 v7, v6, v7, v8
	v_lshlrev_b32_e32 v6, 5, v4
	v_ashrrev_i16_sdwa v1, v12, sext(v1) dst_sel:DWORD dst_unused:UNUSED_PAD src0_sel:DWORD src1_sel:BYTE_0
	v_and_b32_e32 v8, 32, v6
	v_bfe_i32 v6, v1, 0, 16
	v_add_lshl_u32 v1, v8, v6, 1
	v_lshl_add_u32 v128, v7, 11, v1
	v_lshl_add_u32 v130, v3, 11, v1
	v_bfe_i32 v1, v10, 27, 1
	v_lshrrev_b32_e32 v1, 22, v1
	v_add_u32_e32 v1, v0, v1
	v_and_b32_e32 v1, 0xfffffc00, v1
	v_sub_u32_e32 v0, v0, v1
	v_lshrrev_b32_e32 v1, 4, v0
	v_ashrrev_i32_e32 v2, 31, v10
	v_bitop3_b32 v0, v1, v0, 32 bitop3:0x6c
	v_lshrrev_b32_e32 v2, 26, v2
	v_ashrrev_i32_e32 v1, 31, v0
	v_add_u32_e32 v2, v10, v2
	v_lshrrev_b32_e32 v1, 26, v1
	v_ashrrev_i32_e32 v8, 6, v2
	v_add_u32_e32 v1, v0, v1
	v_lshlrev_b32_e32 v2, 3, v8
	v_ashrrev_i32_e32 v7, 6, v1
	v_and_b32_e32 v2, -16, v2
	s_mul_i32 s2, s64, 0xb00000
	v_add_u32_e32 v2, v7, v2
	s_mul_hi_u32 s1, s64, 0xb00000
	s_add_u32 s20, s92, s2
	v_and_b32_e32 v3, 3, v7
	v_lshrrev_b32_e32 v9, 2, v2
	v_lshlrev_b32_e32 v11, 1, v2
	v_and_b32_e32 v1, 0xc0, v1
	s_addc_u32 s21, s93, s1
	s_ashr_i32 s2, s0, 6
	v_and_or_b32 v3, v2, s3, v3
	v_and_b32_e32 v9, 4, v9
	v_and_b32_e32 v11, 24, v11
	v_sub_u32_e32 v0, v0, v1
	s_ashr_i32 s1, s0, 8
	s_lshl_b32 s22, s2, 10
	v_or3_b32 v3, v3, v9, v11
	v_lshlrev_b32_e32 v9, 5, v8
	v_ashrrev_i16_sdwa v0, v12, sext(v0) dst_sel:DWORD dst_unused:UNUSED_PAD src0_sel:DWORD src1_sel:BYTE_0
	v_readlane_b32 s4, v254, 22
	v_and_b32_e32 v11, 32, v9
	v_bfe_i32 v9, v0, 0, 16
	v_readlane_b32 s5, v254, 23
	s_add_u32 s16, s20, s4
	v_add_lshl_u32 v0, v11, v9, 1
	s_addc_u32 s17, s21, s5
	s_add_i32 s23, s22, 0
	v_lshl_add_u32 v132, v3, 11, v0
	s_add_i32 m0, s23, 0x10000
	v_lshl_add_u32 v134, v2, 11, v0
	s_nop 0
	s_nop 0
	s_nop 0
	s_nop 0
	s_nop 0
	s_nop 0
	s_nop 0
	s_nop 0
	s_nop 0
	s_nop 0
	s_nop 0
	s_nop 0
	s_nop 0
	s_nop 0
	s_nop 0
	s_nop 0
	s_nop 0
	s_nop 0
	s_nop 0
	s_nop 0
	s_nop 0
	s_nop 0
	s_nop 0
	s_nop 0
	s_nop 0
	s_nop 0
	s_nop 0
	s_nop 0
	s_nop 0
	s_nop 0
	s_nop 0
	s_nop 0
	s_nop 0
	s_nop 0
	s_nop 0
	s_nop 0
	s_nop 0
	s_nop 0
	s_nop 0
	s_nop 0
	s_nop 0
	s_nop 0
	s_nop 0
	s_nop 0
	s_nop 0
	s_nop 0
	s_nop 0
	s_nop 0
	global_load_lds_dwordx4 v132, s[16:17]
	s_add_i32 m0, s23, 0x12000
	s_add_u32 s4, s16, 0x40000
	global_load_lds_dwordx4 v128, s[16:17]
	s_addc_u32 s5, s17, 0
	s_add_i32 m0, s23, 0x14000
	s_add_i32 s24, s23, 0x2000
	global_load_lds_dwordx4 v132, s[4:5]
	s_add_i32 m0, s23, 0x16000
	s_add_i32 s25, s23, 0x4000
	global_load_lds_dwordx4 v128, s[4:5]
	v_readlane_b32 s4, v254, 26
	s_mov_b32 m0, s23
	v_readlane_b32 s5, v254, 27
	s_add_i32 s26, s23, 0x6000
	v_mov_b32_e32 v133, v169
	v_mov_b32_e32 v129, v169
	s_cmp_eq_u32 s1, 1
	v_lshl_add_u64 v[0:1], s[16:17], 0, v[132:133]
	global_load_lds_dwordx4 v134, s[4:5]
	s_mov_b32 m0, s24
	v_lshl_add_u64 v[2:3], s[16:17], 0, v[128:129]
	global_load_lds_dwordx4 v130, s[4:5]
	v_readlane_b32 s4, v254, 28
	s_mov_b32 m0, s25
	v_readlane_b32 s5, v254, 29
	s_nop 4
	global_load_lds_dwordx4 v134, s[4:5]
	s_mov_b32 m0, s26
	s_nop 0
	global_load_lds_dwordx4 v130, s[4:5]
	s_cselect_b64 s[4:5], -1, 0
	s_cmp_lg_u32 s1, 1
	s_cbranch_scc1 .LBB0_1059
	s_barrier
